# P1 tile order: the 128 cheap k_rope-column tiles moved to the last half-populated round
# baseline (speedup 1.0000x reference)
;     __host__ __device__ bool next(int i, Unit& u) const {
;         const long L = (long)i * G + c; if (L >= nwg) return false;
;         int wgid = (int)L; { const int q = nwg / NXCD, r = nwg % NXCD, xcd = wgid % NXCD, off = wgid / NXCD; wgid = (xcd < r ? xcd * (q + 1) : r * (q + 1) + (xcd - r) * q) + off; }
;         const int nig = WGM * nN, gid = wgid / nig, fm = gid * WGM, gsz = (nM - fm) < WGM ? (nM - fm) : WGM;
;         u.pm = fm + ((wgid % nig) % gsz); u.pn = (wgid % nig) / gsz; return true;
;     }
.LBB0_214:
	s_add_i32 s71, s71, 1
	s_mul_i32 s6, s71, s97
	s_mul_hi_u32 s7, s71, s3
	s_add_i32 s7, s7, s6
	s_mul_i32 s6, s71, s3
	s_add_u32 s42, s6, s84
	s_addc_u32 s43, s7, s78
	v_cmp_gt_i64_e32 vcc, s[42:43], v[150:151]
	v_cmp_lt_i64_e64 s[6:7], s[42:43], v[148:149]
	s_cbranch_vccnz .LBB0_216
	s_and_b32 s9, s42, 7
	s_lshr_b32 s15, s42, 3
	s_lshl_b32 s33, s9, 2
	s_cmp_lt_u32 s15, 0x200
	s_cbranch_scc0 .Lp1map_cheap
	s_lshr_b32 s39, s15, 7
	s_add_i32 s33, s33, s39
	s_lshl_b32 s33, s33, 2
	s_and_b32 s39, s15, 3
	s_add_i32 s40, s33, s39
	s_bfe_u32 s38, s15, 0x50002
	s_cmp_gt_u32 s38, 15
	s_addc_u32 s38, s38, 0
	s_branch .LBB0_216
.Lp1map_cheap:
	s_sub_i32 s15, s15, 0x200
	s_lshr_b32 s39, s15, 2
	s_add_i32 s33, s33, s39
	s_lshl_b32 s33, s33, 2
	s_and_b32 s39, s15, 3
	s_add_i32 s40, s33, s39
	s_mov_b32 s38, 16
